# norm row loop: drop per-row vmcnt(0) that waited for previous row stores before issuing next row loads (wait hoisted to loop preheader)
# speedup vs baseline: 1.0270x; 1.0071x over previous
; __device__ __forceinline__ void norm_phase(const Params& P, LAS unsigned char* lds, int layer, int which, int nrows, int flags, int fprev, int fnext, const float* g2ovr, const float* xsrc, const float* gcp) {
;     ...
;         int2 nsr = make_int2(0, 0); float2 nw = make_float2(0.f, 0.f);
;         if ((flags & 4) && rlo + gw < rhi) { nsr = ((const int2*)(ws + O_SROW))[rlo + gw]; nw = rw[rlo + gw]; }
;         for (int r = rlo + gw; r < rhi; r += ngw) {
.LBB0_1198:
	v_ashrrev_i32_e32 v67, 31, v66
	v_lshlrev_b64 v[120:121], 12, v[66:67]
	v_lshlrev_b32_e32 v135, 7, v66
	v_lshlrev_b64 v[118:119], 3, v[66:67]
	v_or_b32_e32 v120, v102, v120
	s_mov_b64 s[72:73], 0
	s_waitcnt vmcnt(0)
	s_branch .LBB0_1201

; __device__ __forceinline__ void norm_phase(const Params& P, LAS unsigned char* lds, int layer, int which, int nrows, int flags, int fprev, int fnext, const float* g2ovr, const float* xsrc, const float* gcp) {
;     ...
;         for (int r = rlo + gw; r < rhi; r += ngw) {
;             f32x4 v[4];
;             const f32x4* xr = (const f32x4*)((r < SEQ ? xsrc : xres) + (size_t)r * D) + lane;
; #pragma unroll
;             for (int j = 0; j < 4; ++j) v[j] = xr[64 * j];
.LBB0_1201:
	v_add_u32_e32 v136, s66, v98
	v_readlane_b32 s80, v252, 36
	v_readlane_b32 s2, v253, 34
	v_cmp_gt_i32_e64 s[4:5], s33, v136
	v_readlane_b32 s81, v252, 37
	v_readlane_b32 s3, v253, 35
	v_mov_b32_e32 v0, s23
	v_mov_b32_e32 v50, s81
	s_and_b64 vcc, s[2:3], s[4:5]
	v_cndmask_b32_e32 v51, v0, v50, vcc
	v_mov_b32_e32 v0, s22
	v_mov_b32_e32 v50, s80
	v_cndmask_b32_e32 v50, v0, v50, vcc
	v_lshl_add_u64 v[50:51], v[50:51], 0, v[120:121]
	s_waitcnt lgkmcnt(0)
	global_load_dwordx4 v[62:65], v[50:51], off
	global_load_dwordx4 v[58:61], v[50:51], off offset:1024
	global_load_dwordx4 v[54:57], v[50:51], off offset:2048
	s_nop 0
	global_load_dwordx4 v[50:53], v[50:51], off offset:3072
	s_andn2_b64 vcc, exec, s[42:43]
	v_readlane_b32 s82, v252, 38
	v_readlane_b32 s83, v252, 39
	v_readlane_b32 s84, v252, 40
	v_readlane_b32 s85, v252, 41
	v_readlane_b32 s86, v252, 42
	v_readlane_b32 s87, v252, 43
	v_readlane_b32 s88, v252, 44
	v_readlane_b32 s89, v252, 45
	v_readlane_b32 s90, v252, 46
	v_readlane_b32 s91, v252, 47
	v_readlane_b32 s92, v252, 48
	v_readlane_b32 s93, v252, 49
	v_readlane_b32 s94, v252, 50
	v_readlane_b32 s95, v252, 51
	s_cbranch_vccnz .LBB0_1214
	v_add_u32_e32 v66, s66, v103
	v_cmp_gt_i32_e32 vcc, s68, v66
	v_mov_b64_e32 v[122:123], v[116:117]
	v_mov_b64_e32 v[124:125], v[74:75]
	s_and_saveexec_b64 s[6:7], vcc
	s_cbranch_execz .LBB0_1204
	v_ashrrev_i32_e32 v67, 31, v66
	v_readlane_b32 s2, v250, 25
	v_lshlrev_b64 v[66:67], 3, v[66:67]
	v_readlane_b32 s3, v250, 26
	s_nop 1
	v_lshl_add_u64 v[68:69], s[2:3], 0, v[66:67]
	v_lshl_add_u64 v[66:67], s[60:61], 0, v[66:67]
	global_load_dwordx2 v[124:125], v[68:69], off
	global_load_dwordx2 v[122:123], v[66:67], off
